# k=2: q/k-row and LoRA-input row passes moved to the workgroups without a gMLP chunk
# speedup vs baseline: 1.0392x; 1.0060x over previous
; __device__ __forceinline__ void qk_rows(CArgs& a, int l, int gw, int ngw, int lane) {
;     ...
;     float gq[16], gk[16];
;     load16f(a.in[12] + l * 64 + 16 * part, gq); load16f(a.in[13] + l * 64 + 16 * part, gk);
;     for (int row = gw; row < M; row += ngw) {
; __global__ void __launch_bounds__(512, 2) mega_fwd(Args a_) {
;     ...
;                 for (int u = ti.bid; u < Mr / 128; u += ti.nblk) gmlp_unit(ti, a, l, u, lds);
;                 qk_rows(a, l, gw, ngw, lane);
;                 lora_in_rows(a, l, gw, ngw, lane);
;                 } break;
.LBB0_449:
	s_sub_i32 s3, s0, s10
	s_cmp_lt_i32 s3, 64
	s_cbranch_scc1 .Lrows_default
	s_cmp_lt_i32 s2, s10
	s_cbranch_scc1 .Lrows_none
	s_sub_i32 s2, s2, s10
	s_mov_b32 s0, s3
	v_readlane_b32 s3, v255, 42
	s_lshl_b32 s48, s2, 3
	s_lshl_b32 s80, s0, 3
	s_nop 1
	s_add_i32 s48, s48, s3
	s_branch .Lrows_default
.Lrows_none:
	s_movk_i32 s48, 0x4800

; __global__ void __launch_bounds__(512, 2) mega_fwd(Args a_) {
;     ...
;         TI ti; ti.tid = wsv * 64 + (int)__builtin_amdgcn_mbcnt_hi(~0u, __builtin_amdgcn_mbcnt_lo(~0u, 0u)); ti.bid = blockIdx.x; ti.nblk = gridDim.x;
;         asm volatile("" : "+v"(ti.tid)); asm volatile("" : "+s"(ti.bid)); asm volatile("" : "+s"(ti.nblk));
;         const int tid = ti.tid, lane = tid & 63, wv = __builtin_amdgcn_readfirstlane(tid >> 6);
;         const int gw = ti.bid * 8 + wv, ngw = ti.nblk * 8;
;     ...
;                 for (int u = ti.bid; u < Mr / 128; u += ti.nblk) gmlp_unit(ti, a, l, u, lds);
;                 qk_rows(a, l, gw, ngw, lane);
;                 lora_in_rows(a, l, gw, ngw, lane);
;                 } break;
.LBB0_510:
	v_readlane_b32 s2, v255, 2
	v_readlane_b32 s0, v254, 0
	s_nop 3
	s_lshl_b32 s80, s0, 3
	s_mov_b64 s[4:5], 0
	s_mov_b32 s52, s14
	v_readlane_b32 s34, v255, 45
	v_readlane_b32 s36, v255, 46
